# prologue weight-conversion and zero-fill 16-byte stores device-scope
# baseline (speedup 1.0000x reference)
; #define LAS __attribute__((address_space(3)))
; __device__ __forceinline__ unsigned cvt_pk_bf16(float lo, float hi) { const f32x2 v = {lo, hi}; return __builtin_bit_cast(unsigned, __builtin_convertvector(v, bf16v2)); }
; __device__ __forceinline__ int perm_slot(int c) { return ((c >> 2) & 1) * 16 + (c >> 3) * 4 + (c & 3); }
; __device__ __forceinline__ int rowmap(int id, int n) {
;     ...
;   if (id == 1) { const int d = n < 416 ? n : n + 96, g = d >> 5; const bool pm = g < 12 || (g >= 16 && g < 32) || (g >= 40 && g < 56); return pm ? (d & ~31) + perm_slot(d & 31) : d; }
; __device__ __forceinline__ void wt_job(const float* __restrict__ W, int K, int N, bf16_t* __restrict__ Wt, int ldo, int mapid, const float* __restrict__ gain, int rot) {
;     ...
;     for (int h2 = 0; h2 < 2; ++h2) { const int j = (tid >> 8) + 2 * h2, t = t0 + j;
;       if (t < tot) { const int k0 = (t % ntk) * 64, n0 = (t / ntk) * 32, n = (tid & 255) >> 3, kc = tid & 7; LAS const float* s = tile + j * 2080 + n * 65 + kc * 8; u32x4 w;
;         w.x = cvt_pk_bf16(s[0], s[1]); w.y = cvt_pk_bf16(s[2], s[3]); w.z = cvt_pk_bf16(s[4], s[5]); w.w = cvt_pk_bf16(s[6], s[7]);
;         *(u32x4*)(Wt + (size_t)rowmap(mapid, n0 + n) * ldo + k0 + kc * 8) = w; } }
.LBB0_39:
	v_add_u32_e32 v16, s43, v21
	v_cmp_gt_i32_e32 vcc, s76, v16
	v_lshlrev_b32_e32 v14, 1, v20
	s_waitcnt lgkmcnt(0)
	s_barrier
	s_and_saveexec_b64 s[38:39], vcc
	s_cbranch_execz .LBB0_41
	v_ashrrev_i32_e32 v15, 31, v16
	v_lshrrev_b32_e32 v15, 28, v15
	v_add_u32_e32 v15, v16, v15
	v_and_b32_e32 v17, 0x3fffff0, v15
	v_lshlrev_b32_e32 v15, 1, v15
	v_sub_u32_e32 v17, v16, v17
	v_and_or_b32 v15, v15, s77, v24
	v_lshlrev_b32_e32 v36, 6, v17
	v_add_u32_e32 v17, 0x60, v15
	v_cmp_gt_i32_e32 vcc, s78, v15
	ds_read2_b32 v[28:29], v27 offset1:1
	ds_read2_b32 v[30:31], v27 offset0:2 offset1:3
	ds_read2_b32 v[38:39], v27 offset0:4 offset1:5
	ds_read2_b32 v[40:41], v27 offset0:6 offset1:7
	v_cndmask_b32_e32 v15, v17, v15, vcc
	v_ashrrev_i32_e32 v17, 5, v15
	v_and_b32_e32 v37, 0x7ffffff0, v17
	v_cmp_gt_i32_e32 vcc, 12, v17
	v_cmp_eq_u32_e64 s[0:1], 16, v37
	v_subrev_u32_e32 v17, 40, v17
	s_or_b64 s[0:1], vcc, s[0:1]
	v_cmp_gt_u32_e32 vcc, 16, v17
	v_lshlrev_b32_e32 v17, 2, v15
	v_lshrrev_b32_e32 v37, 1, v15
	s_waitcnt lgkmcnt(3)
	v_cvt_pk_bf16_f32 v28, v28, v29
	s_waitcnt lgkmcnt(2)
	v_cvt_pk_bf16_f32 v29, v30, v31
	s_waitcnt lgkmcnt(1)
	v_cvt_pk_bf16_f32 v30, v38, v39
	v_and_b32_e32 v17, 16, v17
	v_and_b32_e32 v37, 12, v37
	v_and_b32_e32 v38, 0xffffffe3, v15
	v_or3_b32 v17, v37, v38, v17
	s_or_b64 vcc, s[0:1], vcc
	v_cndmask_b32_e32 v38, v15, v17, vcc
	v_ashrrev_i32_e32 v39, 31, v38
	v_lshlrev_b64 v[38:39], 11, v[38:39]
	v_lshl_add_u64 v[38:39], s[70:71], 0, v[38:39]
	v_ashrrev_i32_e32 v37, 31, v36
	v_lshl_add_u64 v[36:37], v[36:37], 1, v[38:39]
	v_mov_b32_e32 v15, v19
	s_waitcnt lgkmcnt(0)
	v_cvt_pk_bf16_f32 v31, v40, v41
	v_lshl_add_u64 v[36:37], v[36:37], 0, v[14:15]
	global_store_dwordx4 v[36:37], v[28:31], off sc1
.LBB0_41:
	s_or_b64 exec, exec, s[38:39]
	v_add_u32_e32 v15, 2, v16
	v_cmp_gt_i32_e32 vcc, s76, v15
	s_and_saveexec_b64 s[38:39], vcc
	s_cbranch_execz .LBB0_26
	v_ashrrev_i32_e32 v16, 31, v15
	v_lshrrev_b32_e32 v16, 28, v16
	v_add_u32_e32 v17, v15, v16
	v_and_b32_e32 v16, 0x3fffff0, v17
	v_sub_u32_e32 v15, v15, v16
	v_lshlrev_b32_e32 v16, 6, v15
	v_add_u32_e32 v15, 0x4100, v27
	v_add_u32_e32 v30, 0x4108, v27
	v_add_u32_e32 v36, 0x4110, v27
	v_add_u32_e32 v38, 0x4118, v27
	ds_read2_b32 v[28:29], v15 offset1:1
	ds_read2_b32 v[30:31], v30 offset1:1
	ds_read2_b32 v[36:37], v36 offset1:1
	ds_read2_b32 v[38:39], v38 offset1:1
	v_lshlrev_b32_e32 v15, 1, v17
	v_and_or_b32 v15, v15, s77, v24
	v_add_u32_e32 v17, 0x60, v15
	v_cmp_gt_i32_e32 vcc, s78, v15
	s_waitcnt lgkmcnt(3)
	v_cvt_pk_bf16_f32 v28, v28, v29
	s_waitcnt lgkmcnt(2)
	v_cvt_pk_bf16_f32 v29, v30, v31
	v_cndmask_b32_e32 v15, v17, v15, vcc
	v_ashrrev_i32_e32 v17, 5, v15
	s_waitcnt lgkmcnt(1)
	v_cvt_pk_bf16_f32 v30, v36, v37
	v_and_b32_e32 v36, 0x7ffffff0, v17
	v_cmp_gt_i32_e32 vcc, 12, v17
	v_cmp_eq_u32_e64 s[0:1], 16, v36
	v_subrev_u32_e32 v17, 40, v17
	s_or_b64 s[0:1], vcc, s[0:1]
	v_cmp_gt_u32_e32 vcc, 16, v17
	v_lshlrev_b32_e32 v17, 2, v15
	v_lshrrev_b32_e32 v36, 1, v15
	v_and_b32_e32 v17, 16, v17
	v_and_b32_e32 v36, 12, v36
	v_and_b32_e32 v37, 0xffffffe3, v15
	v_or3_b32 v17, v36, v37, v17
	s_or_b64 vcc, s[0:1], vcc
	v_cndmask_b32_e32 v36, v15, v17, vcc
	v_ashrrev_i32_e32 v37, 31, v36
	v_lshlrev_b64 v[36:37], 11, v[36:37]
	v_lshl_add_u64 v[36:37], s[70:71], 0, v[36:37]
	v_ashrrev_i32_e32 v17, 31, v16
	v_lshl_add_u64 v[16:17], v[16:17], 1, v[36:37]
	v_mov_b32_e32 v15, v19
	s_waitcnt lgkmcnt(0)
	v_cvt_pk_bf16_f32 v31, v38, v39
	v_lshl_add_u64 v[14:15], v[16:17], 0, v[14:15]
	global_store_dwordx4 v[14:15], v[28:31], off sc1
	s_branch .LBB0_26

; #define LAS __attribute__((address_space(3)))
; __device__ __forceinline__ unsigned cvt_pk_bf16(float lo, float hi) { const f32x2 v = {lo, hi}; return __builtin_bit_cast(unsigned, __builtin_convertvector(v, bf16v2)); }
; __device__ __forceinline__ int perm_slot(int c) { return ((c >> 2) & 1) * 16 + (c >> 3) * 4 + (c & 3); }
; __device__ __forceinline__ int rowmap(int id, int n) {
;     ...
;   const int cc = n & 127; return (n >> 7) * 256 + (id == 3 ? 128 : 0) + (cc & ~31) + perm_slot(cc & 31);
; __device__ __forceinline__ void wt_job(const float* __restrict__ W, int K, int N, bf16_t* __restrict__ Wt, int ldo, int mapid, const float* __restrict__ gain, int rot) {
;     ...
;     for (int h2 = 0; h2 < 2; ++h2) { const int j = (tid >> 8) + 2 * h2, t = t0 + j;
;       if (t < tot) { const int k0 = (t % ntk) * 64, n0 = (t / ntk) * 32, n = (tid & 255) >> 3, kc = tid & 7; LAS const float* s = tile + j * 2080 + n * 65 + kc * 8; u32x4 w;
;         w.x = cvt_pk_bf16(s[0], s[1]); w.y = cvt_pk_bf16(s[2], s[3]); w.z = cvt_pk_bf16(s[4], s[5]); w.w = cvt_pk_bf16(s[6], s[7]);
;         *(u32x4*)(Wt + (size_t)rowmap(mapid, n0 + n) * ldo + k0 + kc * 8) = w; } }
.LBB0_58:
	v_add_u32_e32 v16, s93, v21
	v_cmp_gt_i32_e32 vcc, s81, v16
	v_lshlrev_b32_e32 v14, 1, v20
	s_waitcnt lgkmcnt(0)
	s_barrier
	s_and_saveexec_b64 s[42:43], vcc
	s_cbranch_execz .LBB0_60
	v_ashrrev_i32_e32 v15, 31, v16
	v_lshrrev_b32_e32 v15, 28, v15
	v_add_u32_e32 v15, v16, v15
	v_ashrrev_i32_e32 v17, 4, v15
	v_and_b32_e32 v15, 0x3fffff0, v15
	ds_read2_b32 v[28:29], v26 offset1:1
	ds_read2_b32 v[30:31], v26 offset0:2 offset1:3
	ds_read2_b32 v[38:39], v26 offset0:4 offset1:5
	ds_read2_b32 v[40:41], v26 offset0:6 offset1:7
	v_sub_u32_e32 v15, v16, v15
	v_lshlrev_b32_e32 v36, 6, v15
	v_lshlrev_b32_e32 v15, 5, v17
	v_lshlrev_b32_e32 v17, 6, v17
	v_and_b32_e32 v17, 0xffffff00, v17
	v_bitop3_b32 v15, v15, s82, v22 bitop3:0xc8
	s_waitcnt lgkmcnt(3)
	v_cvt_pk_bf16_f32 v28, v28, v29
	s_waitcnt lgkmcnt(2)
	v_cvt_pk_bf16_f32 v29, v30, v31
	s_waitcnt lgkmcnt(1)
	v_cvt_pk_bf16_f32 v30, v38, v39
	v_or3_b32 v38, v17, v15, v23
	v_ashrrev_i32_e32 v39, 31, v38
	v_lshlrev_b64 v[38:39], 11, v[38:39]
	v_lshl_add_u64 v[38:39], s[38:39], 0, v[38:39]
	v_ashrrev_i32_e32 v37, 31, v36
	v_lshl_add_u64 v[36:37], v[36:37], 1, v[38:39]
	v_mov_b32_e32 v15, v19
	s_waitcnt lgkmcnt(0)
	v_cvt_pk_bf16_f32 v31, v40, v41
	v_lshl_add_u64 v[36:37], v[36:37], 0, v[14:15]
	global_store_dwordx4 v[36:37], v[28:31], off sc1
.LBB0_60:
	s_or_b64 exec, exec, s[42:43]
	v_add_u32_e32 v15, 2, v16
	v_cmp_gt_i32_e32 vcc, s81, v15
	s_and_saveexec_b64 s[42:43], vcc
	s_cbranch_execz .LBB0_45
	v_ashrrev_i32_e32 v16, 31, v15
	v_lshrrev_b32_e32 v16, 28, v16
	v_add_u32_e32 v16, v15, v16
	v_ashrrev_i32_e32 v17, 4, v16
	v_and_b32_e32 v16, 0x3fffff0, v16
	v_sub_u32_e32 v15, v15, v16
	v_lshlrev_b32_e32 v16, 6, v15
	v_add_u32_e32 v15, 0x4100, v26
	v_add_u32_e32 v36, 0x4110, v26
	v_add_u32_e32 v38, 0x4118, v26
	v_add_u32_e32 v27, 0x4108, v26
	ds_read2_b32 v[28:29], v15 offset1:1
	ds_read2_b32 v[30:31], v27 offset1:1
	ds_read2_b32 v[36:37], v36 offset1:1
	ds_read2_b32 v[38:39], v38 offset1:1
	v_lshlrev_b32_e32 v15, 5, v17
	v_lshlrev_b32_e32 v17, 6, v17
	v_and_b32_e32 v17, 0xffffff00, v17
	v_bitop3_b32 v15, v15, s82, v22 bitop3:0xc8
	s_waitcnt lgkmcnt(3)
	v_cvt_pk_bf16_f32 v28, v28, v29
	s_waitcnt lgkmcnt(2)
	v_cvt_pk_bf16_f32 v29, v30, v31
	s_waitcnt lgkmcnt(1)
	v_cvt_pk_bf16_f32 v30, v36, v37
	v_or3_b32 v36, v17, v15, v23
	v_ashrrev_i32_e32 v37, 31, v36
	v_lshlrev_b64 v[36:37], 11, v[36:37]
	v_lshl_add_u64 v[36:37], s[38:39], 0, v[36:37]
	v_ashrrev_i32_e32 v17, 31, v16
	v_lshl_add_u64 v[16:17], v[16:17], 1, v[36:37]
	v_mov_b32_e32 v15, v19
	s_waitcnt lgkmcnt(0)
	v_cvt_pk_bf16_f32 v31, v38, v39
	v_lshl_add_u64 v[14:15], v[16:17], 0, v[14:15]
	global_store_dwordx4 v[14:15], v[28:31], off sc1
	s_branch .LBB0_45

; #define LAS __attribute__((address_space(3)))
; __device__ __forceinline__ unsigned cvt_pk_bf16(float lo, float hi) { const f32x2 v = {lo, hi}; return __builtin_bit_cast(unsigned, __builtin_convertvector(v, bf16v2)); }
; __device__ __forceinline__ void wt_job(const float* __restrict__ W, int K, int N, bf16_t* __restrict__ Wt, int ldo, int mapid, const float* __restrict__ gain, int rot) {
;     ...
;     for (int h2 = 0; h2 < 2; ++h2) { const int j = (tid >> 8) + 2 * h2, t = t0 + j;
;       if (t < tot) { const int k0 = (t % ntk) * 64, n0 = (t / ntk) * 32, n = (tid & 255) >> 3, kc = tid & 7; LAS const float* s = tile + j * 2080 + n * 65 + kc * 8; u32x4 w;
;         w.x = cvt_pk_bf16(s[0], s[1]); w.y = cvt_pk_bf16(s[2], s[3]); w.z = cvt_pk_bf16(s[4], s[5]); w.w = cvt_pk_bf16(s[6], s[7]);
;         *(u32x4*)(Wt + (size_t)rowmap(mapid, n0 + n) * ldo + k0 + kc * 8) = w; } }
.LBB0_96:
	v_add_u32_e32 v14, s45, v21
	v_cmp_gt_i32_e32 vcc, s81, v14
	v_lshlrev_b32_e32 v18, 1, v22
	s_waitcnt lgkmcnt(0)
	s_barrier
	s_and_saveexec_b64 s[38:39], vcc
	s_cbranch_execz .LBB0_98
	v_mul_hi_i32 v15, v14, s83
	v_lshrrev_b32_e32 v16, 31, v15
	v_ashrrev_i32_e32 v15, 3, v15
	v_add_u32_e32 v15, v15, v16
	v_mul_lo_u32 v16, v15, 44
	v_sub_u32_e32 v27, v14, v16
	ds_read2_b32 v[16:17], v26 offset1:1
	ds_read2_b32 v[30:31], v26 offset0:2 offset1:3
	ds_read2_b32 v[36:37], v26 offset0:4 offset1:5
	ds_read2_b32 v[38:39], v26 offset0:6 offset1:7
	v_lshlrev_b32_e32 v40, 6, v27
	s_waitcnt lgkmcnt(3)
	v_cvt_pk_bf16_f32 v28, v16, v17
	v_lshl_or_b32 v15, v15, 5, v23
	v_mov_b64_e32 v[16:17], s[36:37]
	v_mad_i64_i32 v[16:17], s[40:41], v15, s84, v[16:17]
	v_ashrrev_i32_e32 v41, 31, v40
	v_lshl_add_u64 v[16:17], v[40:41], 1, v[16:17]
	s_waitcnt lgkmcnt(2)
	v_cvt_pk_bf16_f32 v29, v30, v31
	s_waitcnt lgkmcnt(1)
	v_cvt_pk_bf16_f32 v30, v36, v37
	s_waitcnt lgkmcnt(0)
	v_cvt_pk_bf16_f32 v31, v38, v39
	v_lshl_add_u64 v[16:17], v[16:17], 0, v[18:19]
	global_store_dwordx4 v[16:17], v[28:31], off sc1
.LBB0_98:
	s_or_b64 exec, exec, s[38:39]
	v_add_u32_e32 v14, 2, v14
	v_cmp_gt_i32_e32 vcc, s81, v14
	s_and_saveexec_b64 s[38:39], vcc
	s_cbranch_execz .LBB0_83
	v_mul_hi_i32 v15, v14, s83
	v_lshrrev_b32_e32 v16, 31, v15
	v_ashrrev_i32_e32 v15, 3, v15
	v_add_u32_e32 v27, v15, v16
	v_mul_lo_u32 v15, v27, 44
	v_sub_u32_e32 v36, v14, v15
	v_add_u32_e32 v14, 0x4100, v26
	v_add_u32_e32 v16, 0x4108, v26
	v_add_u32_e32 v28, 0x4110, v26
	v_add_u32_e32 v30, 0x4118, v26
	ds_read2_b32 v[14:15], v14 offset1:1
	ds_read2_b32 v[16:17], v16 offset1:1
	ds_read2_b32 v[28:29], v28 offset1:1
	ds_read2_b32 v[30:31], v30 offset1:1
	v_lshlrev_b32_e32 v36, 6, v36
	s_waitcnt lgkmcnt(3)
	v_cvt_pk_bf16_f32 v14, v14, v15
	s_waitcnt lgkmcnt(2)
	v_cvt_pk_bf16_f32 v15, v16, v17
	s_waitcnt lgkmcnt(1)
	v_cvt_pk_bf16_f32 v16, v28, v29
	v_lshl_or_b32 v27, v27, 5, v23
	v_mov_b64_e32 v[28:29], s[36:37]
	v_mad_i64_i32 v[28:29], s[40:41], v27, s84, v[28:29]
	v_ashrrev_i32_e32 v37, 31, v36
	v_lshl_add_u64 v[28:29], v[36:37], 1, v[28:29]
	s_waitcnt lgkmcnt(0)
	v_cvt_pk_bf16_f32 v17, v30, v31
	v_lshl_add_u64 v[28:29], v[28:29], 0, v[18:19]
	global_store_dwordx4 v[28:29], v[14:17], off sc1
	s_branch .LBB0_83

; #define LAS __attribute__((address_space(3)))
; __device__ __forceinline__ unsigned cvt_pk_bf16(float lo, float hi) { const f32x2 v = {lo, hi}; return __builtin_bit_cast(unsigned, __builtin_convertvector(v, bf16v2)); }
; __device__ __forceinline__ void wt_job(const float* __restrict__ W, int K, int N, bf16_t* __restrict__ Wt, int ldo, int mapid, const float* __restrict__ gain, int rot) {
;     ...
;     for (int h2 = 0; h2 < 2; ++h2) { const int j = (tid >> 8) + 2 * h2, t = t0 + j;
;       if (t < tot) { const int k0 = (t % ntk) * 64, n0 = (t / ntk) * 32, n = (tid & 255) >> 3, kc = tid & 7; LAS const float* s = tile + j * 2080 + n * 65 + kc * 8; u32x4 w;
;         w.x = cvt_pk_bf16(s[0], s[1]); w.y = cvt_pk_bf16(s[2], s[3]); w.z = cvt_pk_bf16(s[4], s[5]); w.w = cvt_pk_bf16(s[6], s[7]);
;         *(u32x4*)(Wt + (size_t)rowmap(mapid, n0 + n) * ldo + k0 + kc * 8) = w; } }
.LBB0_115:
	v_add_u32_e32 v14, s43, v21
	v_cmp_gt_i32_e32 vcc, s85, v14
	v_lshlrev_b32_e32 v18, 1, v22
	s_waitcnt lgkmcnt(0)
	s_barrier
	s_and_saveexec_b64 s[36:37], vcc
	s_cbranch_execz .LBB0_117
	v_ashrrev_i32_e32 v15, 31, v14
	ds_read2_b32 v[28:29], v26 offset1:1
	ds_read2_b32 v[30:31], v26 offset0:2 offset1:3
	ds_read2_b32 v[36:37], v26 offset0:4 offset1:5
	ds_read2_b32 v[38:39], v26 offset0:6 offset1:7
	v_lshrrev_b32_e32 v15, 28, v15
	v_add_u32_e32 v15, v14, v15
	v_and_b32_e32 v16, 0x3fffff0, v15
	v_lshlrev_b32_e32 v15, 1, v15
	s_waitcnt lgkmcnt(3)
	v_cvt_pk_bf16_f32 v28, v28, v29
	s_waitcnt lgkmcnt(2)
	v_cvt_pk_bf16_f32 v29, v30, v31
	s_waitcnt lgkmcnt(1)
	v_cvt_pk_bf16_f32 v30, v36, v37
	v_and_or_b32 v36, v15, s77, v23
	v_sub_u32_e32 v16, v14, v16
	v_ashrrev_i32_e32 v37, 31, v36
	v_lshlrev_b32_e32 v16, 6, v16
	v_lshlrev_b64 v[36:37], 11, v[36:37]
	v_lshl_add_u64 v[36:37], s[34:35], 0, v[36:37]
	v_ashrrev_i32_e32 v17, 31, v16
	v_lshl_add_u64 v[16:17], v[16:17], 1, v[36:37]
	s_waitcnt lgkmcnt(0)
	v_cvt_pk_bf16_f32 v31, v38, v39
	v_lshl_add_u64 v[16:17], v[16:17], 0, v[18:19]
	global_store_dwordx4 v[16:17], v[28:31], off sc1
.LBB0_117:
	s_or_b64 exec, exec, s[36:37]
	v_add_u32_e32 v14, 2, v14
	v_cmp_gt_i32_e32 vcc, s85, v14
	s_and_saveexec_b64 s[36:37], vcc
	s_cbranch_execz .LBB0_102
	v_ashrrev_i32_e32 v15, 31, v14
	v_lshrrev_b32_e32 v15, 28, v15
	v_add_u32_e32 v27, v14, v15
	v_and_b32_e32 v15, 0x3fffff0, v27
	v_sub_u32_e32 v14, v14, v15
	v_lshlrev_b32_e32 v28, 6, v14
	v_add_u32_e32 v14, 0x4100, v26
	v_add_u32_e32 v16, 0x4108, v26
	v_add_u32_e32 v36, 0x4118, v26
	v_add_u32_e32 v29, 0x4110, v26
	ds_read2_b32 v[14:15], v14 offset1:1
	ds_read2_b32 v[16:17], v16 offset1:1
	ds_read2_b32 v[30:31], v29 offset1:1
	ds_read2_b32 v[36:37], v36 offset1:1
	v_lshlrev_b32_e32 v27, 1, v27
	s_waitcnt lgkmcnt(3)
	v_cvt_pk_bf16_f32 v14, v14, v15
	s_waitcnt lgkmcnt(2)
	v_cvt_pk_bf16_f32 v15, v16, v17
	s_waitcnt lgkmcnt(1)
	v_cvt_pk_bf16_f32 v16, v30, v31
	v_and_or_b32 v30, v27, s77, v23
	v_ashrrev_i32_e32 v31, 31, v30
	v_lshlrev_b64 v[30:31], 11, v[30:31]
	v_lshl_add_u64 v[30:31], s[34:35], 0, v[30:31]
	v_ashrrev_i32_e32 v29, 31, v28
	v_lshl_add_u64 v[28:29], v[28:29], 1, v[30:31]
	s_waitcnt lgkmcnt(0)
	v_cvt_pk_bf16_f32 v17, v36, v37
	v_lshl_add_u64 v[28:29], v[28:29], 0, v[18:19]
	global_store_dwordx4 v[28:29], v[14:17], off sc1
	s_branch .LBB0_102

; #define LAS __attribute__((address_space(3)))
; __device__ __forceinline__ unsigned cvt_pk_bf16(float lo, float hi) { const f32x2 v = {lo, hi}; return __builtin_bit_cast(unsigned, __builtin_convertvector(v, bf16v2)); }
; __device__ __forceinline__ int perm_slot(int c) { return ((c >> 2) & 1) * 16 + (c >> 3) * 4 + (c & 3); }
; __device__ __forceinline__ int rowmap(int id, int n) {
;     ...
;   if (id == 4) { const int g = n >> 5; return (g % 3) < 2 ? (n & ~31) + perm_slot(n & 31) : n; }
; __device__ __forceinline__ void wt_job(const float* __restrict__ W, int K, int N, bf16_t* __restrict__ Wt, int ldo, int mapid, const float* __restrict__ gain, int rot) {
;     ...
;     for (int h2 = 0; h2 < 2; ++h2) { const int j = (tid >> 8) + 2 * h2, t = t0 + j;
;       if (t < tot) { const int k0 = (t % ntk) * 64, n0 = (t / ntk) * 32, n = (tid & 255) >> 3, kc = tid & 7; LAS const float* s = tile + j * 2080 + n * 65 + kc * 8; u32x4 w;
;         w.x = cvt_pk_bf16(s[0], s[1]); w.y = cvt_pk_bf16(s[2], s[3]); w.z = cvt_pk_bf16(s[4], s[5]); w.w = cvt_pk_bf16(s[6], s[7]);
;         *(u32x4*)(Wt + (size_t)rowmap(mapid, n0 + n) * ldo + k0 + kc * 8) = w; } }
.LBB0_137:
	v_add_u32_e32 v14, s93, v1
	v_cmp_gt_i32_e32 vcc, s87, v14
	v_lshlrev_b32_e32 v18, 1, v24
	s_waitcnt lgkmcnt(0)
	s_barrier
	s_and_saveexec_b64 s[0:1], vcc
	s_cbranch_execz .LBB0_139
	v_ashrrev_i32_e32 v15, 31, v14
	v_lshrrev_b32_e32 v15, 30, v15
	v_add_u32_e32 v15, v14, v15
	ds_read2_b32 v[16:17], v30 offset1:1
	ds_read2_b32 v[38:39], v30 offset0:2 offset1:3
	ds_read2_b32 v[40:41], v30 offset0:4 offset1:5
	ds_read2_b32 v[42:43], v30 offset0:6 offset1:7
	v_ashrrev_i32_e32 v31, 2, v15
	s_waitcnt lgkmcnt(3)
	v_cvt_pk_bf16_f32 v36, v16, v17
	v_mul_hi_i32 v16, v31, s88
	v_lshrrev_b32_e32 v17, 31, v16
	v_and_b32_e32 v15, 0x3fffffc, v15
	v_add_u32_e32 v16, v16, v17
	v_sub_u32_e32 v15, v14, v15
	v_lshl_add_u32 v16, v16, 1, v16
	v_lshlrev_b32_e32 v44, 6, v15
	v_lshl_or_b32 v15, v31, 5, v23
	v_sub_u32_e32 v16, v31, v16
	v_and_or_b32 v17, v15, s79, v25
	v_cmp_gt_i32_e32 vcc, 2, v16
	v_ashrrev_i32_e32 v45, 31, v44
	s_waitcnt lgkmcnt(2)
	v_cvt_pk_bf16_f32 v37, v38, v39
	v_cndmask_b32_e32 v16, v15, v17, vcc
	v_ashrrev_i32_e32 v17, 31, v16
	v_lshlrev_b64 v[16:17], 9, v[16:17]
	v_lshl_add_u64 v[16:17], s[34:35], 0, v[16:17]
	v_lshl_add_u64 v[16:17], v[44:45], 1, v[16:17]
	s_waitcnt lgkmcnt(1)
	v_cvt_pk_bf16_f32 v38, v40, v41
	s_waitcnt lgkmcnt(0)
	v_cvt_pk_bf16_f32 v39, v42, v43
	v_lshl_add_u64 v[16:17], v[16:17], 0, v[18:19]
	global_store_dwordx4 v[16:17], v[36:39], off sc1
.LBB0_139:
	s_or_b64 exec, exec, s[0:1]
	v_add_u32_e32 v14, 2, v14
	v_cmp_gt_i32_e32 vcc, s87, v14
	s_and_saveexec_b64 s[0:1], vcc
	s_cbranch_execz .LBB0_121
	v_ashrrev_i32_e32 v15, 31, v14
	v_lshrrev_b32_e32 v15, 30, v15
	v_add_u32_e32 v15, v14, v15
	v_ashrrev_i32_e32 v31, 2, v15
	v_and_b32_e32 v15, 0x3fffffc, v15
	v_sub_u32_e32 v40, v14, v15
	v_add_u32_e32 v14, 0x4100, v30
	v_add_u32_e32 v16, 0x4108, v30
	v_add_u32_e32 v36, 0x4110, v30
	v_add_u32_e32 v38, 0x4118, v30
	ds_read2_b32 v[14:15], v14 offset1:1
	ds_read2_b32 v[16:17], v16 offset1:1
	ds_read2_b32 v[36:37], v36 offset1:1
	ds_read2_b32 v[38:39], v38 offset1:1
	v_lshlrev_b32_e32 v40, 6, v40
	s_waitcnt lgkmcnt(3)
	v_cvt_pk_bf16_f32 v14, v14, v15
	s_waitcnt lgkmcnt(2)
	v_cvt_pk_bf16_f32 v15, v16, v17
	s_waitcnt lgkmcnt(1)
	v_cvt_pk_bf16_f32 v16, v36, v37
	v_mul_hi_i32 v37, v31, s88
	s_waitcnt lgkmcnt(0)
	v_cvt_pk_bf16_f32 v17, v38, v39
	v_lshrrev_b32_e32 v38, 31, v37
	v_add_u32_e32 v37, v37, v38
	v_lshl_add_u32 v37, v37, 1, v37
	v_lshl_or_b32 v36, v31, 5, v23
	v_sub_u32_e32 v31, v31, v37
	v_and_or_b32 v37, v36, s79, v25
	v_cmp_gt_i32_e32 vcc, 2, v31
	v_ashrrev_i32_e32 v41, 31, v40
	s_nop 0
	v_cndmask_b32_e32 v36, v36, v37, vcc
	v_ashrrev_i32_e32 v37, 31, v36
	v_lshlrev_b64 v[36:37], 9, v[36:37]
	v_lshl_add_u64 v[36:37], s[34:35], 0, v[36:37]
	v_lshl_add_u64 v[36:37], v[40:41], 1, v[36:37]
	v_lshl_add_u64 v[36:37], v[36:37], 0, v[18:19]
	global_store_dwordx4 v[36:37], v[14:17], off sc1
	s_branch .LBB0_121

; #define LAS __attribute__((address_space(3)))
; __device__ __forceinline__ unsigned cvt_pk_bf16(float lo, float hi) { const f32x2 v = {lo, hi}; return __builtin_bit_cast(unsigned, __builtin_convertvector(v, bf16v2)); }
; __device__ __forceinline__ int perm_slot(int c) { return ((c >> 2) & 1) * 16 + (c >> 3) * 4 + (c & 3); }
; __device__ __forceinline__ int rowmap(int id, int n) {
;     ...
;   if (id == 5) { const int g = n >> 5; return (g & 3) < 2 ? (n & ~31) + perm_slot(n & 31) : n; }
; __device__ __forceinline__ void wt_job(const float* __restrict__ W, int K, int N, bf16_t* __restrict__ Wt, int ldo, int mapid, const float* __restrict__ gain, int rot) {
;     ...
;     for (int h2 = 0; h2 < 2; ++h2) { const int j = (tid >> 8) + 2 * h2, t = t0 + j;
;       if (t < tot) { const int k0 = (t % ntk) * 64, n0 = (t / ntk) * 32, n = (tid & 255) >> 3, kc = tid & 7; LAS const float* s = tile + j * 2080 + n * 65 + kc * 8; u32x4 w;
;         w.x = cvt_pk_bf16(s[0], s[1]); w.y = cvt_pk_bf16(s[2], s[3]); w.z = cvt_pk_bf16(s[4], s[5]); w.w = cvt_pk_bf16(s[6], s[7]);
;         *(u32x4*)(Wt + (size_t)rowmap(mapid, n0 + n) * ldo + k0 + kc * 8) = w; } }
.LBB0_161:
	v_add_u32_e32 v14, s6, v1
	v_cmp_gt_i32_e32 vcc, 48, v14
	v_lshlrev_b32_e32 v18, 1, v24
	s_waitcnt lgkmcnt(0)
	s_barrier
	s_and_saveexec_b64 s[0:1], vcc
	s_cbranch_execz .LBB0_163
	v_lshrrev_b32_e32 v15, 31, v14
	v_add_u32_e32 v15, v14, v15
	v_ashrrev_i32_e32 v31, 1, v15
	v_and_b32_e32 v15, 0x3fffffe, v15
	ds_read2_b32 v[16:17], v30 offset1:1
	ds_read2_b32 v[38:39], v30 offset0:2 offset1:3
	ds_read2_b32 v[40:41], v30 offset0:4 offset1:5
	ds_read2_b32 v[42:43], v30 offset0:6 offset1:7
	v_sub_u32_e32 v15, v14, v15
	v_lshlrev_b32_e32 v44, 6, v15
	s_waitcnt lgkmcnt(3)
	v_cvt_pk_bf16_f32 v36, v16, v17
	v_lshl_or_b32 v15, v31, 5, v23
	v_and_b32_e32 v16, 2, v31
	v_and_or_b32 v17, v15, s90, v25
	v_cmp_eq_u32_e32 vcc, 0, v16
	v_ashrrev_i32_e32 v45, 31, v44
	s_waitcnt lgkmcnt(2)
	v_cvt_pk_bf16_f32 v37, v38, v39
	v_cndmask_b32_e32 v16, v15, v17, vcc
	v_ashrrev_i32_e32 v17, 31, v16
	v_lshlrev_b64 v[16:17], 9, v[16:17]
	v_lshl_add_u64 v[16:17], s[36:37], 0, v[16:17]
	v_lshl_add_u64 v[16:17], v[44:45], 1, v[16:17]
	s_waitcnt lgkmcnt(1)
	v_cvt_pk_bf16_f32 v38, v40, v41
	s_waitcnt lgkmcnt(0)
	v_cvt_pk_bf16_f32 v39, v42, v43
	v_lshl_add_u64 v[16:17], v[16:17], 0, v[18:19]
	global_store_dwordx4 v[16:17], v[36:39], off sc1
.LBB0_163:
	s_or_b64 exec, exec, s[0:1]
	v_add_u32_e32 v14, 2, v14
	v_cmp_gt_i32_e32 vcc, 48, v14
	s_and_saveexec_b64 s[0:1], vcc
	s_cbranch_execz .LBB0_145
	v_lshrrev_b32_e32 v15, 31, v14
	v_add_u32_e32 v15, v14, v15
	v_ashrrev_i32_e32 v31, 1, v15
	v_and_b32_e32 v15, 0x3fffffe, v15
	v_sub_u32_e32 v40, v14, v15
	v_add_u32_e32 v14, 0x4100, v30
	v_add_u32_e32 v16, 0x4108, v30
	v_add_u32_e32 v36, 0x4110, v30
	v_add_u32_e32 v38, 0x4118, v30
	ds_read2_b32 v[14:15], v14 offset1:1
	ds_read2_b32 v[16:17], v16 offset1:1
	ds_read2_b32 v[36:37], v36 offset1:1
	ds_read2_b32 v[38:39], v38 offset1:1
	v_lshlrev_b32_e32 v40, 6, v40
	s_waitcnt lgkmcnt(3)
	v_cvt_pk_bf16_f32 v14, v14, v15
	s_waitcnt lgkmcnt(2)
	v_cvt_pk_bf16_f32 v15, v16, v17
	s_waitcnt lgkmcnt(1)
	v_cvt_pk_bf16_f32 v16, v36, v37
	v_lshl_or_b32 v36, v31, 5, v23
	v_and_b32_e32 v31, 2, v31
	v_and_or_b32 v37, v36, s90, v25
	v_cmp_eq_u32_e32 vcc, 0, v31
	v_ashrrev_i32_e32 v41, 31, v40
	s_waitcnt lgkmcnt(0)
	v_cvt_pk_bf16_f32 v17, v38, v39
	v_cndmask_b32_e32 v36, v36, v37, vcc
	v_ashrrev_i32_e32 v37, 31, v36
	v_lshlrev_b64 v[36:37], 9, v[36:37]
	v_lshl_add_u64 v[36:37], s[36:37], 0, v[36:37]
	v_lshl_add_u64 v[36:37], v[40:41], 1, v[36:37]
	v_lshl_add_u64 v[36:37], v[36:37], 0, v[18:19]
	global_store_dwordx4 v[36:37], v[14:17], off sc1
	s_branch .LBB0_145

; __device__ __forceinline__ int ltid() { return launder((int)threadIdx.x); }
; __device__ __forceinline__ void zero_rows(bf16_t* p, int rows, int rowelems, int ld) {
;   const int cpr = rowelems / 8, tot = rows * cpr;
;   for (int i = blockIdx.x * 512 + ltid(); i < tot; i += gridDim.x * 512) { const int r = i / cpr, c = i % cpr; *(u32x4*)(p + (size_t)r * ld + c * 8) = (u32x4){0u, 0u, 0u, 0u}; }
; }
; __device__ __forceinline__ void prologue(const Params& P) {
;     ...
;     zero_rows(win + 416 * 1024, 96, 1024, 1024); zero_rows(win + 1920 * 1024, 128, 1024, 1024);
.LBB0_169:
	v_ashrrev_i32_e32 v3, 31, v1
	v_lshrrev_b32_e32 v3, 25, v3
	v_add_u32_e32 v3, v1, v3
	v_ashrrev_i32_e32 v4, 7, v3
	v_ashrrev_i32_e32 v5, 31, v4
	v_lshlrev_b32_e32 v3, 10, v4
	v_add_u32_e32 v1, s50, v1
	v_lshlrev_b64 v[4:5], 11, v[4:5]
	v_sub_u32_e32 v6, v2, v3
	v_cmp_lt_i32_e32 vcc, s92, v1
	v_lshl_add_u64 v[4:5], s[38:39], 0, v[4:5]
	v_ashrrev_i32_e32 v7, 31, v6
	s_or_b64 s[40:41], vcc, s[40:41]
	v_add_u32_e32 v2, s6, v2
	v_lshl_add_u64 v[4:5], v[6:7], 1, v[4:5]
	global_store_dwordx4 v[4:5], v[32:35], off sc1
	s_andn2_b64 exec, exec, s[40:41]
	s_cbranch_execnz .LBB0_169

; __device__ __forceinline__ int ltid() { return launder((int)threadIdx.x); }
; __device__ __forceinline__ void zero_rows(bf16_t* p, int rows, int rowelems, int ld) {
;   const int cpr = rowelems / 8, tot = rows * cpr;
;   for (int i = blockIdx.x * 512 + ltid(); i < tot; i += gridDim.x * 512) { const int r = i / cpr, c = i % cpr; *(u32x4*)(p + (size_t)r * ld + c * 8) = (u32x4){0u, 0u, 0u, 0u}; }
; }
; __device__ __forceinline__ void prologue(const Params& P) {
;     ...
;     zero_rows(win + 416 * 1024, 96, 1024, 1024); zero_rows(win + 1920 * 1024, 128, 1024, 1024);
.LBB0_172:
	v_ashrrev_i32_e32 v3, 31, v1
	v_lshrrev_b32_e32 v3, 25, v3
	v_add_u32_e32 v3, v1, v3
	v_ashrrev_i32_e32 v4, 7, v3
	v_ashrrev_i32_e32 v5, 31, v4
	v_lshlrev_b32_e32 v3, 10, v4
	v_add_u32_e32 v1, s50, v1
	s_movk_i32 s40, 0x3fff
	v_lshlrev_b64 v[4:5], 11, v[4:5]
	v_sub_u32_e32 v6, v2, v3
	v_cmp_lt_i32_e32 vcc, s40, v1
	v_lshl_add_u64 v[4:5], s[20:21], 0, v[4:5]
	v_ashrrev_i32_e32 v7, 31, v6
	s_or_b64 s[38:39], vcc, s[38:39]
	v_add_u32_e32 v2, s6, v2
	v_lshl_add_u64 v[4:5], v[6:7], 1, v[4:5]
	global_store_dwordx4 v[4:5], v[32:35], off sc1
	s_andn2_b64 exec, exec, s[38:39]
	s_cbranch_execnz .LBB0_172

; __device__ __forceinline__ int ltid() { return launder((int)threadIdx.x); }
; __device__ __forceinline__ void zero_rows(bf16_t* p, int rows, int rowelems, int ld) {
;   const int cpr = rowelems / 8, tot = rows * cpr;
;   for (int i = blockIdx.x * 512 + ltid(); i < tot; i += gridDim.x * 512) { const int r = i / cpr, c = i % cpr; *(u32x4*)(p + (size_t)r * ld + c * 8) = (u32x4){0u, 0u, 0u, 0u}; }
; }
; __device__ __forceinline__ void prologue(const Params& P) {
;     ...
;     zero_rows(wqb + 576 * 256, 192, 256, 256); zero_rows(wkvb + 128, 768, 128, 256);
.LBB0_175:
	v_ashrrev_i32_e32 v3, 31, v1
	v_lshrrev_b32_e32 v3, 27, v3
	v_add_u32_e32 v3, v1, v3
	v_ashrrev_i32_e32 v4, 5, v3
	v_ashrrev_i32_e32 v5, 31, v4
	v_lshlrev_b32_e32 v3, 8, v4
	v_add_u32_e32 v1, s50, v1
	s_movk_i32 s38, 0x17ff
	v_lshlrev_b64 v[4:5], 9, v[4:5]
	v_sub_u32_e32 v6, v2, v3
	v_cmp_lt_i32_e32 vcc, s38, v1
	v_lshl_add_u64 v[4:5], s[22:23], 0, v[4:5]
	v_ashrrev_i32_e32 v7, 31, v6
	s_or_b64 s[34:35], vcc, s[34:35]
	v_add_u32_e32 v2, s6, v2
	v_lshl_add_u64 v[4:5], v[6:7], 1, v[4:5]
	global_store_dwordx4 v[4:5], v[32:35], off sc1
	s_andn2_b64 exec, exec, s[34:35]
	s_cbranch_execnz .LBB0_175

; __device__ __forceinline__ int ltid() { return launder((int)threadIdx.x); }
; __device__ __forceinline__ void zero_rows(bf16_t* p, int rows, int rowelems, int ld) {
;   const int cpr = rowelems / 8, tot = rows * cpr;
;   for (int i = blockIdx.x * 512 + ltid(); i < tot; i += gridDim.x * 512) { const int r = i / cpr, c = i % cpr; *(u32x4*)(p + (size_t)r * ld + c * 8) = (u32x4){0u, 0u, 0u, 0u}; }
; }
; __device__ __forceinline__ void prologue(const Params& P) {
;     ...
;     zero_rows(wqb + 576 * 256, 192, 256, 256); zero_rows(wkvb + 128, 768, 128, 256);
.LBB0_178:
	v_ashrrev_i32_e32 v3, 31, v1
	v_lshrrev_b32_e32 v3, 28, v3
	v_add_u32_e32 v3, v1, v3
	v_ashrrev_i32_e32 v4, 4, v3
	v_ashrrev_i32_e32 v5, 31, v4
	v_lshlrev_b32_e32 v3, 7, v4
	v_add_u32_e32 v1, s50, v1
	v_lshlrev_b64 v[4:5], 9, v[4:5]
	v_sub_u32_e32 v6, v2, v3
	v_cmp_lt_i32_e32 vcc, s92, v1
	v_lshl_add_u64 v[4:5], s[36:37], 0, v[4:5]
	v_ashrrev_i32_e32 v7, 31, v6
	s_or_b64 s[22:23], vcc, s[22:23]
	v_add_u32_e32 v2, s6, v2
	v_lshl_add_u64 v[4:5], v[6:7], 1, v[4:5]
	global_store_dwordx4 v[4:5], v[32:35], off offset:256 sc1
	s_andn2_b64 exec, exec, s[22:23]
	s_cbranch_execnz .LBB0_178
	s_branch .LBB0_23

; __device__ __forceinline__ void prologue(const Params& P) {
;     ...
;   zero_rows((bf16_t*)(ws + WS_KA) + 16 * 96, 24, 48 * 96, E * 96); zero_rows((bf16_t*)(ws + WS_VTA) + 16, 24 * 64, 48, E);
.LBB0_181:
	v_mul_hi_i32 v7, v1, s7
	v_lshrrev_b32_e32 v8, 31, v7
	v_ashrrev_i32_e32 v7, 7, v7
	v_add_u32_e32 v7, v7, v8
	v_mul_i32_i24_e32 v10, 0x240, v7
	v_mul_hi_i32_i24_e32 v9, 0x183000, v7
	v_mul_i32_i24_e32 v8, 0x183000, v7
	v_lshlrev_b32_e32 v7, 3, v10
	v_add_u32_e32 v1, s50, v1
	v_sub_u32_e32 v10, v6, v7
	v_cmp_lt_i32_e32 vcc, s8, v1
	v_lshl_add_u64 v[8:9], s[2:3], 0, v[8:9]
	v_ashrrev_i32_e32 v11, 31, v10
	s_or_b64 s[4:5], vcc, s[4:5]
	v_add_u32_e32 v6, s6, v6
	v_lshl_add_u64 v[8:9], v[10:11], 1, v[8:9]
	global_store_dwordx4 v[8:9], v[2:5], off sc1
	s_andn2_b64 exec, exec, s[4:5]
	s_cbranch_execnz .LBB0_181

; __device__ __forceinline__ void prologue(const Params& P) {
;     ...
;   zero_rows((bf16_t*)(ws + WS_KA) + 16 * 96, 24, 48 * 96, E * 96); zero_rows((bf16_t*)(ws + WS_VTA) + 16, 24 * 64, 48, E);
;   zero_rows((bf16_t*)(ws + WS_KD) + 16 * 64, 16, 48 * 64, E * 64); zero_rows((bf16_t*)(ws + WS_VTD) + 16, 16 * 64, 48, E);
;   zero_rows((bf16_t*)(ws + WS_KS) + 16 * 64, 8, 48 * 64, E * 64); zero_rows((bf16_t*)(ws + WS_VTS) + 16, 8 * 64, 48, E);
.LBB0_184:
	v_mul_hi_i32 v7, v1, s5
	v_lshrrev_b32_e32 v10, 31, v7
	v_add_u32_e32 v7, v7, v10
	v_add_u32_e32 v1, s50, v1
	v_mad_u64_u32 v[12:13], s[10:11], v7, s7, v[6:7]
	v_cmp_lt_i32_e32 vcc, s8, v1
	v_mad_i64_i32 v[10:11], s[10:11], v7, s6, v[8:9]
	v_ashrrev_i32_e32 v13, 31, v12
	s_or_b64 s[2:3], vcc, s[2:3]
	v_add_u32_e32 v6, s4, v6
	v_lshl_add_u64 v[10:11], v[12:13], 1, v[10:11]
	global_store_dwordx4 v[10:11], v[2:5], off sc1
	s_andn2_b64 exec, exec, s[2:3]
	s_cbranch_execnz .LBB0_184

; __device__ __forceinline__ void prologue(const Params& P) {
;     ...
;   zero_rows((bf16_t*)(ws + WS_KD) + 16 * 64, 16, 48 * 64, E * 64); zero_rows((bf16_t*)(ws + WS_VTD) + 16, 16 * 64, 48, E);
;   zero_rows((bf16_t*)(ws + WS_KS) + 16 * 64, 8, 48 * 64, E * 64); zero_rows((bf16_t*)(ws + WS_VTS) + 16, 8 * 64, 48, E);
.LBB0_187:
	v_mul_hi_i32 v7, v1, s7
	v_lshrrev_b32_e32 v8, 31, v7
	v_ashrrev_i32_e32 v7, 6, v7
	v_add_u32_e32 v7, v7, v8
	v_mul_i32_i24_e32 v10, 0x180, v7
	v_mul_hi_i32_i24_e32 v9, 0x102000, v7
	v_mul_i32_i24_e32 v8, 0x102000, v7
	v_lshlrev_b32_e32 v7, 3, v10
	v_add_u32_e32 v1, s50, v1
	v_sub_u32_e32 v10, v6, v7
	v_cmp_lt_i32_e32 vcc, s8, v1
	v_lshl_add_u64 v[8:9], s[2:3], 0, v[8:9]
	v_ashrrev_i32_e32 v11, 31, v10
	s_or_b64 s[4:5], vcc, s[4:5]
	v_add_u32_e32 v6, s6, v6
	v_lshl_add_u64 v[8:9], v[10:11], 1, v[8:9]
	global_store_dwordx4 v[8:9], v[2:5], off sc1
	s_andn2_b64 exec, exec, s[4:5]
	s_cbranch_execnz .LBB0_187
